# attention: V fragments read ahead of exps into spare VGPRs, pk_add split, per-segment setprio flips (QK high, softmax/PV low)
# speedup vs baseline: 1.0049x; 1.0049x over previous
; #define ATT_WAIT(n) asm volatile("s_waitcnt vmcnt(" #n ")" ::: "memory")
; #define ATT_BAR() do { asm volatile("s_waitcnt lgkmcnt(0)" ::: "memory"); __builtin_amdgcn_s_barrier(); asm volatile("" ::: "memory"); } while (0)
; #define ATT_ISSUE_K() attn_issue_k(F, KH + (size_t)ATT_TILE((t + 2 < nt) ? t + 2 : nt - 1) * ATT_KB, lds + b2 * ATT_KB)
; __device__ __forceinline__ void attn_unit(const Frame& F, int h, int qb, const float* qw, bool desc) {
;     ...
;         for (int t = 0; t < nt; ++t) {
;             const int tl = ATT_TILE(t), tlp = ATT_TILE(t - 1);
;             ATT_ISSUE_K(); if (t > 0) { ATT_SMPV(tlp, bp); } ATT_WAIT(8); ATT_BAR();
; __device__ __forceinline__ void attn_phase(const Frame& F, const float* qw, const float* kw) {
;     if (F.wave >= 4) __builtin_amdgcn_s_setprio(1);
.LBB0_1006:
	s_setprio 0
	s_min_u32 s89, s72, s45
	s_mul_i32 s0, s89, 0x6000
	s_add_u32 s92, s40, s0
	s_addc_u32 s93, s41, 0
	s_mul_i32 s0, s75, 0x6000
	v_mov_b32_e32 v2, v164
	s_add_i32 s0, s0, 0
	s_add_i32 m0, s0, s56
	s_add_u32 s98, s92, s8
	s_addc_u32 s99, s93, s9
	global_load_lds_dwordx4 v164, s[98:99]
	s_add_u32 s100, s92, s10
	s_addc_u32 s101, s93, s11
	s_add_i32 m0, s0, s57
	s_add_u32 s98, s92, s12
	s_addc_u32 s99, s93, s13
	global_load_lds_dwordx4 v164, s[100:101]
	s_add_i32 m0, s0, s58
	s_cmp_eq_u32 s74, 0
	global_load_lds_dwordx4 v164, s[98:99]
	s_mov_b32 s0, s91
	s_cbranch_scc1 .LBB0_1012
	s_sub_i32 s91, s74, 64
	s_cmp_gt_i32 s91, s70
	s_cbranch_scc1 .LBB0_1011
	s_cmp_le_i32 s74, s1
	s_cbranch_scc1 .LBB0_1010
	v_cmp_lt_i32_e32 vcc, -1, v184
	s_nop 1
	v_cndmask_b32_e32 v98, v167, v98, vcc
	v_cmp_lt_i32_e32 vcc, 31, v184
	s_nop 1
	v_cndmask_b32_e32 v82, v167, v82, vcc
	v_cmp_lt_i32_e32 vcc, 0, v184
	s_nop 1
	v_cndmask_b32_e32 v99, v167, v99, vcc
	v_cmp_lt_i32_e32 vcc, 32, v184
	s_nop 1
	v_cndmask_b32_e32 v83, v167, v83, vcc
	v_cmp_lt_i32_e32 vcc, 1, v184
	s_nop 1
	v_cndmask_b32_e32 v100, v167, v100, vcc
	v_cmp_lt_i32_e32 vcc, 33, v184
	s_nop 1
	v_cndmask_b32_e32 v84, v167, v84, vcc
	v_cmp_lt_i32_e32 vcc, 2, v184
	s_nop 1
	v_cndmask_b32_e32 v101, v167, v101, vcc
	v_cmp_lt_i32_e32 vcc, 34, v184
	s_nop 1
	v_cndmask_b32_e32 v85, v167, v85, vcc
	v_cmp_lt_i32_e32 vcc, 7, v184
	s_nop 1
	v_cndmask_b32_e32 v102, v167, v102, vcc
	v_cmp_lt_i32_e32 vcc, 39, v184
	s_nop 1
	v_cndmask_b32_e32 v86, v167, v86, vcc
	v_cmp_lt_i32_e32 vcc, 8, v184
	s_nop 1
	v_cndmask_b32_e32 v103, v167, v103, vcc
	v_cmp_lt_i32_e32 vcc, 40, v184
	s_nop 1
	v_cndmask_b32_e32 v87, v167, v87, vcc
	v_cmp_lt_i32_e32 vcc, 9, v184
	s_nop 1
	v_cndmask_b32_e32 v104, v167, v104, vcc
	v_cmp_lt_i32_e32 vcc, 41, v184
	s_nop 1
	v_cndmask_b32_e32 v88, v167, v88, vcc
	v_cmp_lt_i32_e32 vcc, 10, v184
	s_nop 1
	v_cndmask_b32_e32 v105, v167, v105, vcc
	v_cmp_lt_i32_e32 vcc, 42, v184
	s_nop 1
	v_cndmask_b32_e32 v89, v167, v89, vcc
	v_cmp_lt_i32_e32 vcc, 15, v184
	s_nop 1
	v_cndmask_b32_e32 v106, v167, v106, vcc
	v_cmp_lt_i32_e32 vcc, 47, v184
	s_nop 1
	v_cndmask_b32_e32 v90, v167, v90, vcc
	v_cmp_lt_i32_e32 vcc, 16, v184
	s_nop 1
	v_cndmask_b32_e32 v107, v167, v107, vcc
	v_cmp_lt_i32_e32 vcc, 48, v184
	s_nop 1
	v_cndmask_b32_e32 v91, v167, v91, vcc
	v_cmp_lt_i32_e32 vcc, 17, v184
	s_nop 1
	v_cndmask_b32_e32 v108, v167, v108, vcc
	v_cmp_lt_i32_e32 vcc, 49, v184
	s_nop 1
	v_cndmask_b32_e32 v92, v167, v92, vcc
	v_cmp_lt_i32_e32 vcc, 18, v184
	s_nop 1
	v_cndmask_b32_e32 v109, v167, v109, vcc
	v_cmp_lt_i32_e32 vcc, 50, v184
	s_nop 1
	v_cndmask_b32_e32 v93, v167, v93, vcc
	v_cmp_lt_i32_e32 vcc, 23, v184
	s_nop 1
	v_cndmask_b32_e32 v110, v167, v110, vcc
	v_cmp_lt_i32_e32 vcc, 55, v184
	s_nop 1
	v_cndmask_b32_e32 v94, v167, v94, vcc
	v_cmp_lt_i32_e32 vcc, 24, v184
	s_nop 1
	v_cndmask_b32_e32 v111, v167, v111, vcc
	v_cmp_lt_i32_e32 vcc, 56, v184
	s_nop 1
	v_cndmask_b32_e32 v95, v167, v95, vcc
	v_cmp_lt_i32_e32 vcc, 25, v184
	s_nop 1
	v_cndmask_b32_e32 v112, v167, v112, vcc
	v_cmp_lt_i32_e32 vcc, 57, v184
	s_nop 1
	v_cndmask_b32_e32 v96, v167, v96, vcc
	v_cmp_lt_i32_e32 vcc, 26, v184
	s_nop 1
	v_cndmask_b32_e32 v113, v167, v113, vcc
	v_cmp_lt_i32_e32 vcc, 58, v184
	s_nop 1
	v_cndmask_b32_e32 v97, v167, v97, vcc
.LBB0_1010:
	s_lshl_b32 s90, s90, 14
	s_add_i32 s90, s90, 0x12000
	v_add_u32_e32 v2, s90, v163
	ds_read_b128 v[222:225], v2
	ds_read_b128 v[226:229], v2 offset:4096
	ds_read_b128 v[230:233], v2 offset:8192
	ds_read_b128 v[234:237], v2 offset:12288
	v_add_u32_e32 v2, s90, v171
	ds_read_b128 v[238:241], v2
	ds_read_b128 v[242:245], v2 offset:4096
	ds_read_b128 v[246:249], v2 offset:8192
	ds_read_b128 v[250:253], v2 offset:12288
	v_exp_f32_e32 v2, v98
	v_exp_f32_e32 v4, v99
	v_exp_f32_e32 v5, v100
	v_exp_f32_e32 v6, v101
	v_add_f32_e32 v7, 0, v2
	v_exp_f32_e32 v8, v102
	v_add_f32_e32 v7, v4, v7
	v_exp_f32_e32 v9, v103
	v_add_f32_e32 v7, v5, v7
	v_exp_f32_e32 v10, v104
	v_add_f32_e32 v7, v6, v7
	v_exp_f32_e32 v11, v105
	v_add_f32_e32 v7, v8, v7
	v_exp_f32_e32 v16, v106
	v_add_f32_e32 v7, v9, v7
	v_exp_f32_e32 v106, v107
	v_add_f32_e32 v7, v10, v7
	v_exp_f32_e32 v107, v108
	v_add_f32_e32 v7, v11, v7
	v_exp_f32_e32 v108, v109
	v_add_f32_e32 v7, v16, v7
	v_exp_f32_e32 v109, v110
	v_add_f32_e32 v7, v106, v7
	v_exp_f32_e32 v110, v111
	v_add_f32_e32 v7, v107, v7
	v_exp_f32_e32 v111, v112
	v_add_f32_e32 v7, v108, v7
	v_exp_f32_e32 v112, v113
	v_add_f32_e32 v7, v109, v7
	v_add_f32_e32 v7, v110, v7
	v_add_f32_e32 v7, v111, v7
	v_cvt_pk_bf16_f32 v4, v2, v4
	v_add_f32_e32 v17, v112, v7
	v_cvt_pk_bf16_f32 v5, v5, v6
	v_cvt_pk_bf16_f32 v6, v8, v9
	v_cvt_pk_bf16_f32 v7, v10, v11
	v_cvt_pk_bf16_f32 v106, v16, v106
	v_cvt_pk_bf16_f32 v107, v107, v108
	v_cvt_pk_bf16_f32 v108, v109, v110
	v_cvt_pk_bf16_f32 v109, v111, v112
	s_waitcnt lgkmcnt(7)
	v_mfma_f32_32x32x16_bf16 v[66:81], v[222:225], v[4:7], v[66:81]
	v_exp_f32_e32 v2, v82
	v_exp_f32_e32 v185, v83
	s_nop 0
	v_add_f32_e32 v199, v2, v185
	s_waitcnt lgkmcnt(6)
	v_mfma_f32_32x32x16_bf16 v[50:65], v[226:229], v[4:7], v[50:65]
	v_exp_f32_e32 v198, v84
	v_exp_f32_e32 v16, v85
	s_nop 0
	v_add_f32_e32 v8, v198, v16
	v_add_f32_e32 v9, v199, v17
	v_add_f32_e32 v201, v8, v9
	s_waitcnt lgkmcnt(5)
	v_mfma_f32_32x32x16_bf16 v[34:49], v[230:233], v[4:7], v[34:49]
	v_exp_f32_e32 v17, v86
	v_exp_f32_e32 v199, v87
	s_nop 0
	v_add_f32_e32 v203, v17, v199
	s_waitcnt lgkmcnt(4)
	v_mfma_f32_32x32x16_bf16 v[18:33], v[234:237], v[4:7], v[18:33]
	v_exp_f32_e32 v202, v88
	v_exp_f32_e32 v200, v89
	s_nop 0
	v_add_f32_e32 v8, v202, v200
	v_add_f32_e32 v9, v203, v201
	v_add_f32_e32 v205, v8, v9
	v_add_u32_e32 v82, s90, v172
	ds_read_b128 v[4:7], v82
	ds_read_b128 v[8:11], v82 offset:4096
	ds_read_b128 v[12:15], v82 offset:8192
	ds_read_b128 v[82:85], v82 offset:12288
	s_waitcnt lgkmcnt(7)
	v_mfma_f32_32x32x16_bf16 v[66:81], v[238:241], v[106:109], v[66:81]
	v_exp_f32_e32 v201, v90
	v_exp_f32_e32 v203, v91
	s_nop 0
	v_add_f32_e32 v207, v201, v203
	s_waitcnt lgkmcnt(6)
	v_mfma_f32_32x32x16_bf16 v[50:65], v[242:245], v[106:109], v[50:65]
	v_exp_f32_e32 v206, v92
	v_exp_f32_e32 v204, v93
	s_nop 0
	v_add_f32_e32 v86, v206, v204
	v_add_f32_e32 v87, v207, v205
	v_add_f32_e32 v111, v86, v87
	s_waitcnt lgkmcnt(5)
	v_mfma_f32_32x32x16_bf16 v[34:49], v[246:249], v[106:109], v[34:49]
	v_exp_f32_e32 v186, v94
	v_exp_f32_e32 v187, v95
	s_nop 0
	v_add_f32_e32 v113, v186, v187
	s_waitcnt lgkmcnt(4)
	v_mfma_f32_32x32x16_bf16 v[18:33], v[250:253], v[106:109], v[18:33]
	v_exp_f32_e32 v112, v96
	v_exp_f32_e32 v110, v97
	s_nop 0
	v_add_f32_e32 v86, v112, v110
	v_add_f32_e32 v87, v113, v111
	v_add_f32_e32 v102, v86, v87
	v_add_u32_e32 v98, s90, v173
	ds_read_b128 v[86:89], v98
	ds_read_b128 v[90:93], v98 offset:4096
	ds_read_b128 v[94:97], v98 offset:8192
	ds_read_b128 v[98:101], v98 offset:12288
	v_add_f32_e32 v178, v178, v102
	v_cvt_pk_bf16_f32 v102, v2, v185
	v_cvt_pk_bf16_f32 v103, v198, v16
	v_cvt_pk_bf16_f32 v104, v17, v199
	v_cvt_pk_bf16_f32 v105, v202, v200
	v_cvt_pk_bf16_f32 v106, v201, v203
	v_cvt_pk_bf16_f32 v107, v206, v204
	v_cvt_pk_bf16_f32 v108, v186, v187
	v_cvt_pk_bf16_f32 v109, v112, v110
	s_waitcnt lgkmcnt(7)
	v_mfma_f32_32x32x16_bf16 v[66:81], v[4:7], v[102:105], v[66:81]
	s_waitcnt lgkmcnt(6)
	v_mfma_f32_32x32x16_bf16 v[50:65], v[8:11], v[102:105], v[50:65]
	s_waitcnt lgkmcnt(5)
	v_mfma_f32_32x32x16_bf16 v[34:49], v[12:15], v[102:105], v[34:49]
	s_waitcnt lgkmcnt(4)
	v_mfma_f32_32x32x16_bf16 v[18:33], v[82:85], v[102:105], v[18:33]
	s_waitcnt lgkmcnt(0)
	v_mfma_f32_32x32x16_bf16 v[66:81], v[86:89], v[106:109], v[66:81]
	v_mfma_f32_32x32x16_bf16 v[50:65], v[90:93], v[106:109], v[50:65]
	v_mfma_f32_32x32x16_bf16 v[34:49], v[94:97], v[106:109], v[34:49]
	v_mfma_f32_32x32x16_bf16 v[18:33], v[98:101], v[106:109], v[18:33]

; #define ATT_WAIT(n) asm volatile("s_waitcnt vmcnt(" #n ")" ::: "memory")
; #define ATT_BAR() do { asm volatile("s_waitcnt lgkmcnt(0)" ::: "memory"); __builtin_amdgcn_s_barrier(); asm volatile("" ::: "memory"); } while (0)
; #define ATT_ISSUE_K() attn_issue_k(F, KH + (size_t)ATT_TILE((t + 2 < nt) ? t + 2 : nt - 1) * ATT_KB, lds + b2 * ATT_KB)
; #define ATT_ISSUE_V() attn_issue_v(F, VT + (size_t)ATT_TILE((t + 2 < nt) ? t + 2 : nt - 1) * ATT_VB, lds + ATT_VBASE + b2 * ATT_VB)
; __device__ __forceinline__ void attn_unit(const Frame& F, int h, int qb, const float* qw, bool desc) {
;     ...
;             ATT_ISSUE_K(); if (t > 0) { ATT_SMPV(tlp, bp); } ATT_WAIT(8); ATT_BAR();
;             ATT_ISSUE_V(); ATT_QK(tl, b0); ATT_WAIT(7); ATT_BAR();
.LBB0_1013:
	s_lshl_b32 s89, s89, 14
	s_add_u32 s92, s42, s89
	s_addc_u32 s93, s43, 0
	s_lshl_b32 s89, s75, 14
	s_waitcnt vmcnt(8)
	s_add_i32 s89, s89, 0
	v_mov_b32_e32 v2, v164
	s_waitcnt lgkmcnt(0)
	s_barrier
	s_setprio 1
	s_add_i32 s89, s89, 0x12000
	s_add_i32 m0, s89, s59
	s_add_u32 s98, s92, s14
	s_addc_u32 s99, s93, s15
	global_load_lds_dwordx4 v164, s[98:99]
	s_add_u32 s100, s92, s16
	s_addc_u32 s101, s93, s17
	s_add_i32 m0, s89, s60
	s_cmp_gt_i32 s90, s70
	global_load_lds_dwordx4 v164, s[100:101]
	s_cbranch_scc1 .LBB0_1015
	s_mul_i32 s89, s0, 0x6000
	v_add_u32_e32 v2, s89, v174
	v_add_u32_e32 v16, s89, v175
	ds_read_b128 v[4:7], v2
	ds_read_b128 v[8:11], v2 offset:12288
	ds_read_b128 v[12:15], v16
	ds_read_b128 v[186:189], v16 offset:12288
	v_add_u32_e32 v17, s89, v176
	v_add_u32_e32 v185, s89, v177
	ds_read_b128 v[190:193], v17
	ds_read_b128 v[194:197], v17 offset:12288
	ds_read_b128 v[198:201], v185
	ds_read_b128 v[202:205], v185 offset:12288
	ds_read_b128 v[206:209], v2 offset:128
	ds_read_b128 v[210:213], v2 offset:12416
	ds_read_b128 v[214:217], v16 offset:128
	ds_read_b128 v[218:221], v16 offset:12416
	s_waitcnt lgkmcnt(8)
	v_mfma_f32_32x32x16_bf16 v[98:113], v[4:7], v[114:117], 0
	v_mfma_f32_32x32x16_bf16 v[98:113], v[12:15], v[118:121], v[98:113]
	v_mfma_f32_32x32x16_bf16 v[82:97], v[8:11], v[114:117], 0
	v_mfma_f32_32x32x16_bf16 v[82:97], v[186:189], v[118:121], v[82:97]
	ds_read_b128 v[4:7], v17 offset:128
	ds_read_b128 v[8:11], v17 offset:12416
	ds_read_b128 v[12:15], v185 offset:128
	ds_read_b128 v[186:189], v185 offset:12416
	s_waitcnt lgkmcnt(8)
	v_mfma_f32_32x32x16_bf16 v[98:113], v[190:193], v[122:125], v[98:113]
	v_mfma_f32_32x32x16_bf16 v[98:113], v[198:201], v[126:129], v[98:113]
	v_mfma_f32_32x32x16_bf16 v[82:97], v[194:197], v[122:125], v[82:97]
	v_mfma_f32_32x32x16_bf16 v[82:97], v[202:205], v[126:129], v[82:97]
	ds_read_b128 v[190:193], v2 offset:256
	ds_read_b128 v[194:197], v2 offset:12544
	ds_read_b128 v[198:201], v16 offset:256
	ds_read_b128 v[202:205], v16 offset:12544
	s_waitcnt lgkmcnt(8)
	v_mfma_f32_32x32x16_bf16 v[98:113], v[206:209], v[130:133], v[98:113]
	v_mfma_f32_32x32x16_bf16 v[98:113], v[214:217], v[134:137], v[98:113]
	v_mfma_f32_32x32x16_bf16 v[82:97], v[210:213], v[130:133], v[82:97]
	v_mfma_f32_32x32x16_bf16 v[82:97], v[218:221], v[134:137], v[82:97]
	ds_read_b128 v[206:209], v17 offset:256
	ds_read_b128 v[210:213], v17 offset:12544
	ds_read_b128 v[214:217], v185 offset:256
	ds_read_b128 v[218:221], v185 offset:12544
	s_waitcnt lgkmcnt(8)
	v_mfma_f32_32x32x16_bf16 v[98:113], v[4:7], v[138:141], v[98:113]
	v_mfma_f32_32x32x16_bf16 v[98:113], v[12:15], v[142:145], v[98:113]
	v_mfma_f32_32x32x16_bf16 v[82:97], v[8:11], v[138:141], v[82:97]
	v_mfma_f32_32x32x16_bf16 v[82:97], v[186:189], v[142:145], v[82:97]
	s_waitcnt lgkmcnt(4)
	v_mfma_f32_32x32x16_bf16 v[98:113], v[190:193], v[146:149], v[98:113]
	v_mfma_f32_32x32x16_bf16 v[98:113], v[198:201], v[154:157], v[98:113]
	v_mfma_f32_32x32x16_bf16 v[82:97], v[194:197], v[146:149], v[82:97]
	v_mfma_f32_32x32x16_bf16 v[82:97], v[202:205], v[154:157], v[82:97]
	s_waitcnt lgkmcnt(0)
	v_mfma_f32_32x32x16_bf16 v[98:113], v[206:209], v[150:153], v[98:113]
	v_mfma_f32_32x32x16_bf16 v[98:113], v[214:217], v[158:161], v[98:113]
	v_mfma_f32_32x32x16_bf16 v[82:97], v[210:213], v[150:153], v[82:97]
	v_mfma_f32_32x32x16_bf16 v[82:97], v[218:221], v[158:161], v[82:97]
	s_branch .LBB0_1016

; __device__ __forceinline__ void attn_unit(const Frame& F, int h, int qb, const float* qw, bool desc) {
;     ...
;         { const int tll = ATT_TILE(nt - 1); ATT_SMPV(tll, bp); }
.LBB0_1021:
	v_exp_f32_e32 v2, v98
	v_exp_f32_e32 v4, v99
	v_exp_f32_e32 v5, v100
	v_exp_f32_e32 v6, v101
	v_add_f32_e32 v7, 0, v2
	v_exp_f32_e32 v8, v102
	v_add_f32_e32 v7, v4, v7
	v_exp_f32_e32 v9, v103
	v_add_f32_e32 v7, v5, v7
	v_exp_f32_e32 v10, v104
	v_add_f32_e32 v7, v6, v7
	v_exp_f32_e32 v11, v105
	v_add_f32_e32 v7, v8, v7
	v_exp_f32_e32 v16, v106
	v_add_f32_e32 v7, v9, v7
	v_exp_f32_e32 v106, v107
	v_add_f32_e32 v7, v10, v7
	v_exp_f32_e32 v107, v108
	v_add_f32_e32 v7, v11, v7
	v_exp_f32_e32 v108, v109
	v_add_f32_e32 v7, v16, v7
	v_exp_f32_e32 v109, v110
	v_add_f32_e32 v7, v106, v7
	v_exp_f32_e32 v110, v111
	v_add_f32_e32 v7, v107, v7
	v_exp_f32_e32 v111, v112
	v_add_f32_e32 v7, v108, v7
	v_exp_f32_e32 v112, v113
	s_lshl_b32 s0, s0, 14
	v_add_f32_e32 v7, v109, v7
	s_add_i32 s0, s0, 0
	v_add_f32_e32 v7, v110, v7
	s_add_i32 s0, s0, 0x12000
	v_add_f32_e32 v7, v111, v7
	v_cvt_pk_bf16_f32 v4, v2, v4
	v_add_u32_e32 v2, s0, v183
	v_add_f32_e32 v17, v112, v7
	v_cvt_pk_bf16_f32 v5, v5, v6
	v_cvt_pk_bf16_f32 v6, v8, v9
	v_cvt_pk_bf16_f32 v7, v10, v11
	ds_read_b128 v[8:11], v2
	ds_read_b128 v[12:15], v2 offset:4096
	ds_read_b128 v[98:101], v2 offset:8192
	ds_read_b128 v[102:105], v2 offset:12288
	v_cvt_pk_bf16_f32 v106, v16, v106
	v_cvt_pk_bf16_f32 v107, v107, v108
	v_cvt_pk_bf16_f32 v108, v109, v110
	v_cvt_pk_bf16_f32 v109, v111, v112
	v_add_u32_e32 v2, s0, v182
	ds_read_b128 v[110:113], v2
	ds_read_b128 v[182:185], v2 offset:4096
	ds_read_b128 v[186:189], v2 offset:8192
	ds_read_b128 v[190:193], v2 offset:12288
	s_waitcnt lgkmcnt(7)
	v_mfma_f32_32x32x16_bf16 v[66:81], v[8:11], v[4:7], v[66:81]
	v_exp_f32_e32 v2, v82
	v_exp_f32_e32 v170, v83
	s_nop 0
	v_add_f32_e32 v195, v2, v170
	s_waitcnt lgkmcnt(6)
	v_mfma_f32_32x32x16_bf16 v[50:65], v[12:15], v[4:7], v[50:65]
	v_exp_f32_e32 v194, v84
	v_exp_f32_e32 v16, v85
	s_nop 0
	v_add_f32_e32 v8, v194, v16
	v_add_f32_e32 v9, v195, v17
	v_add_f32_e32 v197, v8, v9
	s_waitcnt lgkmcnt(5)
	v_mfma_f32_32x32x16_bf16 v[34:49], v[98:101], v[4:7], v[34:49]
	v_exp_f32_e32 v17, v86
	v_exp_f32_e32 v195, v87
	s_nop 0
	v_add_f32_e32 v199, v17, v195
	s_waitcnt lgkmcnt(4)
	v_mfma_f32_32x32x16_bf16 v[18:33], v[102:105], v[4:7], v[18:33]
	v_exp_f32_e32 v198, v88
	v_exp_f32_e32 v196, v89
	s_nop 0
	v_add_f32_e32 v8, v198, v196
	v_add_f32_e32 v9, v199, v197
	v_add_f32_e32 v201, v8, v9
	v_add_u32_e32 v82, s0, v181
	ds_read_b128 v[4:7], v82
	ds_read_b128 v[8:11], v82 offset:4096
	ds_read_b128 v[12:15], v82 offset:8192
	ds_read_b128 v[82:85], v82 offset:12288
	s_waitcnt lgkmcnt(7)
	v_mfma_f32_32x32x16_bf16 v[66:81], v[110:113], v[106:109], v[66:81]
	v_exp_f32_e32 v181, v90
	v_exp_f32_e32 v197, v91
	s_nop 0
	v_add_f32_e32 v203, v181, v197
	s_waitcnt lgkmcnt(6)
	v_mfma_f32_32x32x16_bf16 v[50:65], v[182:185], v[106:109], v[50:65]
	v_exp_f32_e32 v202, v92
	v_exp_f32_e32 v200, v93
	s_nop 0
	v_add_f32_e32 v86, v202, v200
	v_add_f32_e32 v87, v203, v201
	v_add_f32_e32 v111, v86, v87
	s_waitcnt lgkmcnt(5)
	v_mfma_f32_32x32x16_bf16 v[34:49], v[186:189], v[106:109], v[34:49]
	v_exp_f32_e32 v182, v94
	v_exp_f32_e32 v183, v95
	s_nop 0
	v_add_f32_e32 v113, v182, v183
	s_waitcnt lgkmcnt(4)
	v_mfma_f32_32x32x16_bf16 v[18:33], v[190:193], v[106:109], v[18:33]
	v_exp_f32_e32 v112, v96
	v_exp_f32_e32 v110, v97
	s_nop 0
	v_add_f32_e32 v86, v112, v110
	v_add_f32_e32 v87, v113, v111
	v_add_f32_e32 v102, v86, v87
	v_add_u32_e32 v98, s0, v180
	ds_read_b128 v[86:89], v98
	ds_read_b128 v[90:93], v98 offset:4096
	ds_read_b128 v[94:97], v98 offset:8192
	ds_read_b128 v[98:101], v98 offset:12288
	v_add_f32_e32 v178, v178, v102
	v_cvt_pk_bf16_f32 v102, v2, v170
	v_cvt_pk_bf16_f32 v103, v194, v16
	v_cvt_pk_bf16_f32 v104, v17, v195
	v_cvt_pk_bf16_f32 v105, v198, v196
	v_cvt_pk_bf16_f32 v106, v181, v197
	v_cvt_pk_bf16_f32 v107, v202, v200
	v_cvt_pk_bf16_f32 v108, v182, v183
	v_cvt_pk_bf16_f32 v109, v112, v110
	s_waitcnt lgkmcnt(7)
	v_mfma_f32_32x32x16_bf16 v[66:81], v[4:7], v[102:105], v[66:81]
	s_waitcnt lgkmcnt(6)
	v_mfma_f32_32x32x16_bf16 v[50:65], v[8:11], v[102:105], v[50:65]
	s_waitcnt lgkmcnt(5)
	v_mfma_f32_32x32x16_bf16 v[34:49], v[12:15], v[102:105], v[34:49]
	s_waitcnt lgkmcnt(4)
	v_mfma_f32_32x32x16_bf16 v[18:33], v[82:85], v[102:105], v[18:33]
	s_waitcnt lgkmcnt(0)
	v_mfma_f32_32x32x16_bf16 v[66:81], v[86:89], v[106:109], v[66:81]
	v_mfma_f32_32x32x16_bf16 v[50:65], v[90:93], v[106:109], v[50:65]
	v_mfma_f32_32x32x16_bf16 v[34:49], v[94:97], v[106:109], v[34:49]
	v_mfma_f32_32x32x16_bf16 v[18:33], v[98:101], v[106:109], v[18:33]

; #define ATT_WAIT(n) asm volatile("s_waitcnt vmcnt(" #n ")" ::: "memory")
; #define ATT_BAR() do { asm volatile("s_waitcnt lgkmcnt(0)" ::: "memory"); __builtin_amdgcn_s_barrier(); asm volatile("" ::: "memory"); } while (0)
; #define ATT_ISSUE_V() attn_issue_v(F, VT + (size_t)ATT_TILE((t + 2 < nt) ? t + 2 : nt - 1) * ATT_VB, lds + ATT_VBASE + b2 * ATT_VB)
; __device__ __forceinline__ void attn_unit(const Frame& F, int h, int qb, const float* qw, bool desc) {
;     ...
;             ATT_ISSUE_V(); ATT_SMPV(tl, b0); ATT_WAIT(7); ATT_BAR();
.LBB0_1025:
	s_lshl_b32 s0, s73, 14
	s_add_i32 s0, s0, 0x12000
	v_add_u32_e32 v2, s0, v163
	ds_read_b128 v[222:225], v2
	ds_read_b128 v[226:229], v2 offset:4096
	ds_read_b128 v[230:233], v2 offset:8192
	ds_read_b128 v[234:237], v2 offset:12288
	v_add_u32_e32 v2, s0, v171
	ds_read_b128 v[238:241], v2
	ds_read_b128 v[242:245], v2 offset:4096
	ds_read_b128 v[246:249], v2 offset:8192
	ds_read_b128 v[250:253], v2 offset:12288
	v_exp_f32_e32 v2, v98
	v_exp_f32_e32 v4, v99
	v_exp_f32_e32 v5, v100
	v_exp_f32_e32 v6, v101
	v_add_f32_e32 v7, 0, v2
	v_exp_f32_e32 v8, v102
	v_add_f32_e32 v7, v4, v7
	v_exp_f32_e32 v9, v103
	v_add_f32_e32 v7, v5, v7
	v_exp_f32_e32 v10, v104
	v_add_f32_e32 v7, v6, v7
	v_exp_f32_e32 v11, v105
	v_add_f32_e32 v7, v8, v7
	v_exp_f32_e32 v16, v106
	v_add_f32_e32 v7, v9, v7
	v_exp_f32_e32 v106, v107
	v_add_f32_e32 v7, v10, v7
	v_exp_f32_e32 v107, v108
	v_add_f32_e32 v7, v11, v7
	v_exp_f32_e32 v108, v109
	v_add_f32_e32 v7, v16, v7
	v_exp_f32_e32 v109, v110
	v_add_f32_e32 v7, v106, v7
	v_exp_f32_e32 v110, v111
	v_add_f32_e32 v7, v107, v7
	v_exp_f32_e32 v111, v112
	v_add_f32_e32 v7, v108, v7
	v_exp_f32_e32 v112, v113
	v_add_f32_e32 v7, v109, v7
	v_add_f32_e32 v7, v110, v7
	v_add_f32_e32 v7, v111, v7
	v_cvt_pk_bf16_f32 v4, v2, v4
	v_add_f32_e32 v17, v112, v7
	v_cvt_pk_bf16_f32 v5, v5, v6
	v_cvt_pk_bf16_f32 v6, v8, v9
	v_cvt_pk_bf16_f32 v7, v10, v11
	v_cvt_pk_bf16_f32 v106, v16, v106
	v_cvt_pk_bf16_f32 v107, v107, v108
	v_cvt_pk_bf16_f32 v108, v109, v110
	v_cvt_pk_bf16_f32 v109, v111, v112
	s_waitcnt lgkmcnt(7)
	v_mfma_f32_32x32x16_bf16 v[66:81], v[222:225], v[4:7], v[66:81]
	v_exp_f32_e32 v2, v82
	v_exp_f32_e32 v179, v83
	s_nop 0
	v_add_f32_e32 v193, v2, v179
	s_waitcnt lgkmcnt(6)
	v_mfma_f32_32x32x16_bf16 v[50:65], v[226:229], v[4:7], v[50:65]
	v_exp_f32_e32 v192, v84
	v_exp_f32_e32 v16, v85
	s_nop 0
	v_add_f32_e32 v8, v192, v16
	v_add_f32_e32 v9, v193, v17
	v_add_f32_e32 v195, v8, v9
	s_waitcnt lgkmcnt(5)
	v_mfma_f32_32x32x16_bf16 v[34:49], v[230:233], v[4:7], v[34:49]
	v_exp_f32_e32 v17, v86
	v_exp_f32_e32 v193, v87
	s_nop 0
	v_add_f32_e32 v197, v17, v193
	s_waitcnt lgkmcnt(4)
	v_mfma_f32_32x32x16_bf16 v[18:33], v[234:237], v[4:7], v[18:33]
	v_exp_f32_e32 v196, v88
	v_exp_f32_e32 v194, v89
	s_nop 0
	v_add_f32_e32 v8, v196, v194
	v_add_f32_e32 v9, v197, v195
	v_add_f32_e32 v199, v8, v9
	v_add_u32_e32 v82, s0, v172
	ds_read_b128 v[4:7], v82
	ds_read_b128 v[8:11], v82 offset:4096
	ds_read_b128 v[12:15], v82 offset:8192
	ds_read_b128 v[82:85], v82 offset:12288
	s_waitcnt lgkmcnt(7)
	v_mfma_f32_32x32x16_bf16 v[66:81], v[238:241], v[106:109], v[66:81]
	v_exp_f32_e32 v195, v90
	v_exp_f32_e32 v197, v91
	s_nop 0
	v_add_f32_e32 v201, v195, v197
	s_waitcnt lgkmcnt(6)
	v_mfma_f32_32x32x16_bf16 v[50:65], v[242:245], v[106:109], v[50:65]
	v_exp_f32_e32 v200, v92
	v_exp_f32_e32 v198, v93
	s_nop 0
	v_add_f32_e32 v86, v200, v198
	v_add_f32_e32 v87, v201, v199
	v_add_f32_e32 v111, v86, v87
	s_waitcnt lgkmcnt(5)
	v_mfma_f32_32x32x16_bf16 v[34:49], v[246:249], v[106:109], v[34:49]
	v_exp_f32_e32 v180, v94
	v_exp_f32_e32 v181, v95
	s_nop 0
	v_add_f32_e32 v113, v180, v181
	s_waitcnt lgkmcnt(4)
	v_mfma_f32_32x32x16_bf16 v[18:33], v[250:253], v[106:109], v[18:33]
	v_exp_f32_e32 v112, v96
	v_exp_f32_e32 v110, v97
	s_nop 0
	v_add_f32_e32 v86, v112, v110
	v_add_f32_e32 v87, v113, v111
	v_add_f32_e32 v102, v86, v87
	v_add_u32_e32 v98, s0, v173
	ds_read_b128 v[86:89], v98
	ds_read_b128 v[90:93], v98 offset:4096
	ds_read_b128 v[94:97], v98 offset:8192
	ds_read_b128 v[98:101], v98 offset:12288
	v_add_f32_e32 v178, v178, v102
	v_cvt_pk_bf16_f32 v102, v2, v179
	v_cvt_pk_bf16_f32 v103, v192, v16
	v_cvt_pk_bf16_f32 v104, v17, v193
	v_cvt_pk_bf16_f32 v105, v196, v194
	v_cvt_pk_bf16_f32 v106, v195, v197
	v_cvt_pk_bf16_f32 v107, v200, v198
	v_cvt_pk_bf16_f32 v108, v180, v181
	v_cvt_pk_bf16_f32 v109, v112, v110
	s_waitcnt lgkmcnt(7)
	v_mfma_f32_32x32x16_bf16 v[66:81], v[4:7], v[102:105], v[66:81]
	s_waitcnt lgkmcnt(6)
	v_mfma_f32_32x32x16_bf16 v[50:65], v[8:11], v[102:105], v[50:65]
	s_waitcnt lgkmcnt(5)
	v_mfma_f32_32x32x16_bf16 v[34:49], v[12:15], v[102:105], v[34:49]
	s_waitcnt lgkmcnt(4)
	v_mfma_f32_32x32x16_bf16 v[18:33], v[82:85], v[102:105], v[18:33]
	s_waitcnt lgkmcnt(0)
	v_mfma_f32_32x32x16_bf16 v[66:81], v[86:89], v[106:109], v[66:81]
	v_mfma_f32_32x32x16_bf16 v[50:65], v[90:93], v[106:109], v[50:65]
	v_mfma_f32_32x32x16_bf16 v[34:49], v[94:97], v[106:109], v[34:49]
	v_mfma_f32_32x32x16_bf16 v[18:33], v[98:101], v[106:109], v[18:33]

; #define ATT_WAIT(n) asm volatile("s_waitcnt vmcnt(" #n ")" ::: "memory")
; #define ATT_BAR() do { asm volatile("s_waitcnt lgkmcnt(0)" ::: "memory"); __builtin_amdgcn_s_barrier(); asm volatile("" ::: "memory"); } while (0)
; #define ATT_ISSUE_K() attn_issue_k(F, KH + (size_t)ATT_TILE((t + 2 < nt) ? t + 2 : nt - 1) * ATT_KB, lds + b2 * ATT_KB)
; __device__ __forceinline__ void attn_unit(const Frame& F, int h, int qb, const float* qw, bool desc) {
;     ...
;         for (int t = 0; t < nt; ++t) {
;             const int tl = ATT_TILE(t);
;             ATT_ISSUE_K(); ATT_QK(tl, b0); ATT_WAIT(8); ATT_BAR();
.LBB0_1027:
	s_setprio 1
	s_min_u32 s75, s33, s45
	s_mul_i32 s0, s75, 0x6000
	s_add_u32 s0, s40, s0
	s_addc_u32 s1, s41, 0
	s_mul_i32 s88, s74, 0x6000
	v_mov_b32_e32 v2, v164
	s_add_i32 s88, s88, 0
	s_add_i32 m0, s88, s56
	s_add_u32 s98, s0, s8
	s_addc_u32 s99, s1, s9
	global_load_lds_dwordx4 v164, s[98:99]
	s_add_u32 s100, s0, s10
	s_addc_u32 s101, s1, s11
	s_add_i32 m0, s88, s57
	s_add_u32 s98, s0, s12
	s_addc_u32 s99, s1, s13
	global_load_lds_dwordx4 v164, s[100:101]
	s_add_i32 m0, s88, s58
	s_cmp_le_u32 s72, s70
	global_load_lds_dwordx4 v164, s[98:99]
	s_cselect_b64 s[0:1], -1, 0
	s_cmp_gt_u32 s72, s70
	s_cbranch_scc1 .LBB0_1029
	s_mul_i32 s88, s73, 0x6000
	v_add_u32_e32 v2, s88, v174
	v_add_u32_e32 v16, s88, v175
	ds_read_b128 v[4:7], v2
	ds_read_b128 v[8:11], v2 offset:12288
	ds_read_b128 v[12:15], v16
	ds_read_b128 v[180:183], v16 offset:12288
	v_add_u32_e32 v17, s88, v176
	v_add_u32_e32 v179, s88, v177
	ds_read_b128 v[184:187], v17
	ds_read_b128 v[188:191], v17 offset:12288
	ds_read_b128 v[192:195], v179
	ds_read_b128 v[196:199], v179 offset:12288
	ds_read_b128 v[200:203], v2 offset:128
	ds_read_b128 v[204:207], v2 offset:12416
	ds_read_b128 v[208:211], v16 offset:128
	ds_read_b128 v[212:215], v16 offset:12416
	s_waitcnt lgkmcnt(8)
	v_mfma_f32_32x32x16_bf16 v[98:113], v[4:7], v[114:117], 0
	v_mfma_f32_32x32x16_bf16 v[98:113], v[12:15], v[118:121], v[98:113]
	v_mfma_f32_32x32x16_bf16 v[82:97], v[8:11], v[114:117], 0
	v_mfma_f32_32x32x16_bf16 v[82:97], v[180:183], v[118:121], v[82:97]
	ds_read_b128 v[4:7], v17 offset:128
	ds_read_b128 v[8:11], v17 offset:12416
	ds_read_b128 v[12:15], v179 offset:128
	ds_read_b128 v[180:183], v179 offset:12416
	s_waitcnt lgkmcnt(8)
	v_mfma_f32_32x32x16_bf16 v[98:113], v[184:187], v[122:125], v[98:113]
	v_mfma_f32_32x32x16_bf16 v[98:113], v[192:195], v[126:129], v[98:113]
	v_mfma_f32_32x32x16_bf16 v[82:97], v[188:191], v[122:125], v[82:97]
	v_mfma_f32_32x32x16_bf16 v[82:97], v[196:199], v[126:129], v[82:97]
	ds_read_b128 v[184:187], v2 offset:256
	ds_read_b128 v[188:191], v2 offset:12544
	ds_read_b128 v[192:195], v16 offset:256
	ds_read_b128 v[196:199], v16 offset:12544
	s_waitcnt lgkmcnt(8)
	v_mfma_f32_32x32x16_bf16 v[98:113], v[200:203], v[130:133], v[98:113]
	v_mfma_f32_32x32x16_bf16 v[98:113], v[208:211], v[134:137], v[98:113]
	v_mfma_f32_32x32x16_bf16 v[82:97], v[204:207], v[130:133], v[82:97]
	v_mfma_f32_32x32x16_bf16 v[82:97], v[212:215], v[134:137], v[82:97]
	ds_read_b128 v[200:203], v17 offset:256
	ds_read_b128 v[204:207], v17 offset:12544
	ds_read_b128 v[208:211], v179 offset:256
	ds_read_b128 v[212:215], v179 offset:12544
	s_waitcnt lgkmcnt(8)
	v_mfma_f32_32x32x16_bf16 v[98:113], v[4:7], v[138:141], v[98:113]
	v_mfma_f32_32x32x16_bf16 v[98:113], v[12:15], v[142:145], v[98:113]
	v_mfma_f32_32x32x16_bf16 v[82:97], v[8:11], v[138:141], v[82:97]
	v_mfma_f32_32x32x16_bf16 v[82:97], v[180:183], v[142:145], v[82:97]
	s_waitcnt lgkmcnt(4)
	v_mfma_f32_32x32x16_bf16 v[98:113], v[184:187], v[146:149], v[98:113]
	v_mfma_f32_32x32x16_bf16 v[98:113], v[192:195], v[154:157], v[98:113]
	v_mfma_f32_32x32x16_bf16 v[82:97], v[188:191], v[146:149], v[82:97]
	v_mfma_f32_32x32x16_bf16 v[82:97], v[196:199], v[154:157], v[82:97]
	s_waitcnt lgkmcnt(0)
	v_mfma_f32_32x32x16_bf16 v[98:113], v[200:203], v[150:153], v[98:113]
	v_mfma_f32_32x32x16_bf16 v[98:113], v[208:211], v[158:161], v[98:113]
	v_mfma_f32_32x32x16_bf16 v[82:97], v[204:207], v[150:153], v[82:97]
	v_mfma_f32_32x32x16_bf16 v[82:97], v[212:215], v[158:161], v[82:97]
	s_branch .LBB0_1030

; #define ATT_WAIT(n) asm volatile("s_waitcnt vmcnt(" #n ")" ::: "memory")
; #define ATT_BAR() do { asm volatile("s_waitcnt lgkmcnt(0)" ::: "memory"); __builtin_amdgcn_s_barrier(); asm volatile("" ::: "memory"); } while (0)
; #define ATT_ISSUE_K() attn_issue_k(F, KH + (size_t)ATT_TILE((t + 2 < nt) ? t + 2 : nt - 1) * ATT_KB, lds + b2 * ATT_KB)
; #define ATT_ISSUE_V() attn_issue_v(F, VT + (size_t)ATT_TILE((t + 2 < nt) ? t + 2 : nt - 1) * ATT_VB, lds + ATT_VBASE + b2 * ATT_VB)
; __device__ __forceinline__ void attn_unit(const Frame& F, int h, int qb, const float* qw, bool desc) {
;     ...
;             ATT_ISSUE_K(); ATT_QK(tl, b0); ATT_WAIT(8); ATT_BAR();
;             ATT_ISSUE_V(); ATT_SMPV(tl, b0); ATT_WAIT(7); ATT_BAR();
.LBB0_1030:
	s_lshl_b32 s75, s75, 14
	s_add_u32 s88, s42, s75
	s_addc_u32 s89, s43, 0
	s_lshl_b32 s75, s74, 14
	s_waitcnt vmcnt(8)
	s_add_i32 s75, s75, 0
	v_mov_b32_e32 v2, v164
	s_waitcnt lgkmcnt(0)
	s_barrier
	s_setprio 0
	s_add_i32 s75, s75, 0x12000
	s_add_i32 m0, s75, s59
	s_add_u32 s98, s88, s14
	s_addc_u32 s99, s89, s15
	global_load_lds_dwordx4 v164, s[98:99]
	s_add_u32 s100, s88, s16
	s_addc_u32 s101, s89, s17
	s_add_i32 m0, s75, s60
	s_andn2_b64 vcc, exec, s[0:1]
	global_load_lds_dwordx4 v164, s[100:101]
	s_cbranch_vccnz .LBB0_1026
	s_add_i32 s0, s72, 47
	s_cmp_le_u32 s0, s6
	s_cbranch_scc1 .LBB0_1025
	v_cmp_lt_i32_e32 vcc, -1, v170
	s_nop 1
	v_cndmask_b32_e32 v98, v167, v98, vcc
	v_cmp_lt_i32_e32 vcc, 31, v170
	s_nop 1
	v_cndmask_b32_e32 v82, v167, v82, vcc
	v_cmp_lt_i32_e32 vcc, 0, v170
	s_nop 1
	v_cndmask_b32_e32 v99, v167, v99, vcc
	v_cmp_lt_i32_e32 vcc, 32, v170
	s_nop 1
	v_cndmask_b32_e32 v83, v167, v83, vcc
	v_cmp_lt_i32_e32 vcc, 1, v170
	s_nop 1
	v_cndmask_b32_e32 v100, v167, v100, vcc
	v_cmp_lt_i32_e32 vcc, 33, v170
	s_nop 1
	v_cndmask_b32_e32 v84, v167, v84, vcc
	v_cmp_lt_i32_e32 vcc, 2, v170
	s_nop 1
	v_cndmask_b32_e32 v101, v167, v101, vcc
	v_cmp_lt_i32_e32 vcc, 34, v170
	s_nop 1
	v_cndmask_b32_e32 v85, v167, v85, vcc
	v_cmp_lt_i32_e32 vcc, 7, v170
	s_nop 1
	v_cndmask_b32_e32 v102, v167, v102, vcc
	v_cmp_lt_i32_e32 vcc, 39, v170
	s_nop 1
	v_cndmask_b32_e32 v86, v167, v86, vcc
	v_cmp_lt_i32_e32 vcc, 8, v170
	s_nop 1
	v_cndmask_b32_e32 v103, v167, v103, vcc
	v_cmp_lt_i32_e32 vcc, 40, v170
	s_nop 1
	v_cndmask_b32_e32 v87, v167, v87, vcc
	v_cmp_lt_i32_e32 vcc, 9, v170
	s_nop 1
	v_cndmask_b32_e32 v104, v167, v104, vcc
	v_cmp_lt_i32_e32 vcc, 41, v170
	s_nop 1
	v_cndmask_b32_e32 v88, v167, v88, vcc
	v_cmp_lt_i32_e32 vcc, 10, v170
	s_nop 1
	v_cndmask_b32_e32 v105, v167, v105, vcc
	v_cmp_lt_i32_e32 vcc, 42, v170
	s_nop 1
	v_cndmask_b32_e32 v89, v167, v89, vcc
	v_cmp_lt_i32_e32 vcc, 15, v170
	s_nop 1
	v_cndmask_b32_e32 v106, v167, v106, vcc
	v_cmp_lt_i32_e32 vcc, 47, v170
	s_nop 1
	v_cndmask_b32_e32 v90, v167, v90, vcc
	v_cmp_lt_i32_e32 vcc, 16, v170
	s_nop 1
	v_cndmask_b32_e32 v107, v167, v107, vcc
	v_cmp_lt_i32_e32 vcc, 48, v170
	s_nop 1
	v_cndmask_b32_e32 v91, v167, v91, vcc
	v_cmp_lt_i32_e32 vcc, 17, v170
	s_nop 1
	v_cndmask_b32_e32 v108, v167, v108, vcc
	v_cmp_lt_i32_e32 vcc, 49, v170
	s_nop 1
	v_cndmask_b32_e32 v92, v167, v92, vcc
	v_cmp_lt_i32_e32 vcc, 18, v170
	s_nop 1
	v_cndmask_b32_e32 v109, v167, v109, vcc
	v_cmp_lt_i32_e32 vcc, 50, v170
	s_nop 1
	v_cndmask_b32_e32 v93, v167, v93, vcc
	v_cmp_lt_i32_e32 vcc, 23, v170
	s_nop 1
	v_cndmask_b32_e32 v110, v167, v110, vcc
	v_cmp_lt_i32_e32 vcc, 55, v170
	s_nop 1
	v_cndmask_b32_e32 v94, v167, v94, vcc
	v_cmp_lt_i32_e32 vcc, 24, v170
	s_nop 1
	v_cndmask_b32_e32 v111, v167, v111, vcc
	v_cmp_lt_i32_e32 vcc, 56, v170
	s_nop 1
	v_cndmask_b32_e32 v95, v167, v95, vcc
	v_cmp_lt_i32_e32 vcc, 25, v170
	s_nop 1
	v_cndmask_b32_e32 v112, v167, v112, vcc
	v_cmp_lt_i32_e32 vcc, 57, v170
	s_nop 1
	v_cndmask_b32_e32 v96, v167, v96, vcc
	v_cmp_lt_i32_e32 vcc, 26, v170
	s_nop 1
	v_cndmask_b32_e32 v113, v167, v113, vcc
	v_cmp_lt_i32_e32 vcc, 58, v170
	s_nop 1
	v_cndmask_b32_e32 v97, v167, v97, vcc
	s_branch .LBB0_1025
